# LB1: phases 16-19 are XCD-local in row space (P17 rows remapped to the XCD owning the row group), so the barriers after phases 16,17,18 skip the cross-XCD level (no wbl2 / top-level atomic)
# speedup vs baseline: 1.0081x; 1.0064x over previous
;     ...
;     for (int i = F.tid; i < 1024; i += NWAVES * 64) {
;         gl[i] = gw_[i];
; #pragma unroll
;         for (int cnd = 0; cnd < 3; ++cnd) {
;             float sh, sc;
;             if (from_partials) { sh = ada_b[layer * 6144 + offsh + i]; sc = ada_b[layer * 6144 + offsc + i];
;                 float ph[ADA_KS], pc[ADA_KS];
; #pragma unroll
;                 for (int ks = 0; ks < ADA_KS; ++ks) { const float* p = modp + ((size_t)(ks * 2 + layer) * 3 + cnd) * 6144; ph[ks] = p[offsh + i]; pc[ks] = p[offsc + i]; }
; #pragma unroll
;                 for (int ks = 0; ks < ADA_KS; ++ks) { sh += ph[ks]; sc += pc[ks]; } }
;             else { sh = mod[(layer * 3 + cnd) * 6144 + offsh + i]; sc = mod[(layer * 3 + cnd) * 6144 + offsc + i]; }
;             scl[cnd * 1024 + i] = 1.f + sc; shl[cnd * 1024 + i] = sh;
;         }
;     }
.LBB0_40:
	v_lshlrev_b32_e32 v220, 2, v2
	v_lshlrev_b32_e32 v221, 2, v3
	global_load_dword v236, v220, s[4:5]
	global_load_dword v237, v221, s[4:5]
	v_add_u32_e32 v222, s12, v220
	v_add_u32_e32 v223, s12, v221
	global_load_dword v228, v222, s[8:9] offset:-4096
	global_load_dword v229, v223, s[8:9] offset:-4096
	global_load_dword v230, v222, s[8:9]
	global_load_dword v231, v223, s[8:9]
	v_add_u32_e32 v222, s13, v220
	v_add_u32_e32 v223, s13, v221
	global_load_dword v232, v222, s[8:9] offset:-4096
	global_load_dword v233, v223, s[8:9] offset:-4096
	global_load_dword v234, v222, s[8:9]
	global_load_dword v235, v223, s[8:9]
	v_add_u32_e32 v222, s14, v220
	v_add_u32_e32 v223, s14, v221
	global_load_dword v238, v222, s[8:9] offset:-4096
	global_load_dword v239, v223, s[8:9] offset:-4096
	global_load_dword v240, v222, s[8:9]
	global_load_dword v241, v223, s[8:9]
	v_add_u32_e32 v5, -2, v5
	v_add_u32_e32 v224, 0x400, v2
	v_add_u32_e32 v225, 0x400, v3
	v_lshl_add_u32 v226, v224, 2, 0
	v_lshl_add_u32 v227, v225, 2, 0
	v_cmp_eq_u32_e32 vcc, 0, v5
	s_or_b64 s[10:11], vcc, s[10:11]
	s_waitcnt vmcnt(0)
	ds_write2st64_b32 v6, v236, v237 offset1:8
	v_add_f32_e32 v230, 1.0, v230
	v_add_f32_e32 v231, 1.0, v231
	ds_write2st64_b32 v6, v230, v231 offset0:16 offset1:24
	ds_write2st64_b32 v6, v228, v229 offset0:64 offset1:72
	v_add_f32_e32 v234, 1.0, v234
	v_add_f32_e32 v235, 1.0, v235
	ds_write_b32 v226, v234 offset:4096
	ds_write_b32 v227, v235 offset:4096
	ds_write_b32 v226, v232 offset:16384
	ds_write_b32 v227, v233 offset:16384
	v_add_f32_e32 v240, 1.0, v240
	v_add_f32_e32 v241, 1.0, v241
	ds_write_b32 v220, v240 offset:12288
	ds_write_b32 v221, v241 offset:12288
	ds_write_b32 v220, v238 offset:24576
	ds_write_b32 v221, v239 offset:24576
	v_add_u32_e32 v6, 0x1000, v6
	v_mov_b32_e32 v2, v224
	v_mov_b32_e32 v3, v225
	s_andn2_b64 exec, exec, s[10:11]
	s_cbranch_execnz .LBB0_40
	s_nop 0
	s_nop 0
	s_nop 0
	s_nop 0
	s_nop 0
	s_nop 0
	s_nop 0
	s_nop 0
	s_nop 0
	s_nop 0
	s_nop 0
	s_nop 0
	s_nop 0
	s_nop 0
	s_nop 0
	s_nop 0
	s_nop 0
	s_nop 0
	s_nop 0
	s_nop 0
	s_nop 0
	s_or_b64 exec, exec, s[10:11]
	v_cmp_ne_u32_e32 vcc, v0, v4
	v_lshl_add_u32 v2, v4, 9, v170
	s_orn2_b64 s[8:9], vcc, exec

; #define GAS __attribute__((address_space(1)))
;     ...
;     const int gw = F.vcu * NWAVES + F.wave, NGW = F.G * NWAVES;
;     for (int m = gw; m < nrows; m += NGW) {
;         const float* xrow = m < ML ? src_lat + (size_t)m * DM : src_ctx + (size_t)(m - ML) * DM;
;         const int cnd = m < SEQ ? 0 : (m < ML ? 1 : 2);
;         const GAS f32x4* xr = (const GAS f32x4*)xrow + F.lane;
;         f32x4 v[4]; float s = 0.f;
;         if (lat_bf16 && m < ML) {
.LBB0_45:
	s_or_b64 exec, exec, s[2:3]
	v_readlane_b32 s2, v243, 20
	s_lshr_b32 s3, s2, 5
	s_lshl_b32 s3, s3, 11
	s_and_b32 s2, s2, 31
	s_lshl_b32 s2, s2, 3
	s_add_i32 s2, s2, s3
	v_readlane_b32 s3, v243, 24
	s_add_i32 s2, s2, s3
	s_cmpk_gt_i32 s2, 0x3fff
	s_waitcnt lgkmcnt(0)
	s_barrier
	s_cbranch_scc1 .LBB0_48
	v_lshl_add_u32 v46, v172, 4, 0
	v_readlane_b32 s3, v243, 18
	s_waitcnt vmcnt(0)
	ds_read_b128 v[2:5], v46
	ds_read_b128 v[6:9], v46 offset:1024
	ds_read_b128 v[10:13], v46 offset:2048
	ds_read_b128 v[14:17], v46 offset:3072
	s_movk_i32 s6, 0x100
	s_ashr_i32 s3, s2, 31
	s_lshl_b64 s[4:5], s[2:3], 11
	s_add_u32 s4, s80, s4
	v_lshlrev_b32_e32 v0, 3, v172
	s_addc_u32 s5, s81, s5
	v_lshl_add_u64 v[18:19], s[4:5], 0, v[0:1]
	s_mov_b64 s[4:5], 0xd900000
	s_ashr_i32 s7, s6, 31
	v_lshl_add_u64 v[26:27], v[18:19], 0, s[4:5]
	s_lshl_b64 s[8:9], s[6:7], 11
	s_mov_b32 s11, 0xffff0000
	s_mov_b32 s12, 0xf800000
	s_movk_i32 s13, 0x7fff
	global_load_dwordx2 v[18:19], v[26:27], off
	global_load_dwordx2 v[20:21], v[26:27], off offset:512
	global_load_dwordx2 v[22:23], v[26:27], off offset:1024
	global_load_dwordx2 v[24:25], v[26:27], off offset:1536
	s_waitcnt vmcnt(0)
	s_branch .Lp17_body

; #define GAS __attribute__((address_space(1)))
;     ...
;     for (int m = gw; m < nrows; m += NGW) {
;         const float* xrow = m < ML ? src_lat + (size_t)m * DM : src_ctx + (size_t)(m - ML) * DM;
;         const int cnd = m < SEQ ? 0 : (m < ML ? 1 : 2);
;         const GAS f32x4* xr = (const GAS f32x4*)xrow + F.lane;
;         f32x4 v[4]; float s = 0.f;
;         if (lat_bf16 && m < ML) {
;             const GAS v2u* xb = (const GAS v2u*)((const bf16*)src_lat + (size_t)m * DM) + F.lane;
;             v2u w[4];
; #pragma unroll
;             for (int j = 0; j < 4; ++j) w[j] = xb[64 * j];
; #pragma unroll
;             for (int j = 0; j < 4; ++j) v[j] = f32x4{bflo(w[j].x), bfhi(w[j].x), bflo(w[j].y), bfhi(w[j].y)};
;         } else {
; #pragma unroll
;             for (int j = 0; j < 4; ++j) v[j] = xr[64 * j];
;         }
.Lp17_body:
	s_cmpk_lt_i32 s2, 0x2000
	s_cselect_b32 s3, 0, 0x1000
	s_add_i32 s2, s2, s6
	s_and_b32 s98, s2, 0x700
	v_mov_b64_e32 v[220:221], v[18:19]
	v_mov_b64_e32 v[222:223], v[20:21]
	v_mov_b64_e32 v[224:225], v[22:23]
	v_mov_b64_e32 v[226:227], v[24:25]
	v_mov_b64_e32 v[228:229], v[26:27]
	v_lshl_add_u64 v[26:27], v[26:27], 0, s[8:9]
	s_cbranch_scc0 .Lp17_nopf
	global_load_dwordx2 v[18:19], v[26:27], off
	global_load_dwordx2 v[20:21], v[26:27], off offset:512
	global_load_dwordx2 v[22:23], v[26:27], off offset:1024
	global_load_dwordx2 v[24:25], v[26:27], off offset:1536

; __device__ __forceinline__ unsigned xb_ld(unsigned* p)              { return __hip_atomic_load(p, __ATOMIC_RELAXED, __HIP_MEMORY_SCOPE_AGENT); }
; __device__ __forceinline__ unsigned xb_add(unsigned* p, unsigned v) { return __hip_atomic_fetch_add(p, v, __ATOMIC_RELAXED, __HIP_MEMORY_SCOPE_AGENT); }
; #define XB_SPIN(cond, bar) do { unsigned _sp = 0; while (cond) { __builtin_amdgcn_s_sleep(0);     \
;     if ((++_sp & 255u) == 0u) { if (xb_ld(&(bar)[XB_TMO])) break; if (_sp > XB_SPIN_CAP) { atomicAdd(&(bar)[XB_TMO], 1u); break; } } } } while (0)
; __device__ __forceinline__ void xcd_barrier(const XcdBarrier& b) {
;     ...
;         const unsigned old = xb_add(&bar[XB_XSUB(b.x)], 1u);
;         const unsigned gen = old / nloc;
;         if (old + 1u == (gen + 1u) * nloc) {
;             __builtin_amdgcn_fence(__ATOMIC_RELEASE, "agent");
;             asm volatile("s_waitcnt vmcnt(0)" ::: "memory");
;             const unsigned og = xb_add(&bar[XB_TOP], 1u);
;             const unsigned tg = og / nx;
;             if (og + 1u == (tg + 1u) * nx) xb_add(&bar[XB_TOPGEN], 1u);
;             else XB_SPIN(xb_ld(&bar[XB_TOPGEN]) == tg, bar);
.LBB0_1263:
	v_readlane_b32 s4, v243, 16
	s_sub_i32 s4, s4, 16
	s_cmp_lt_u32 s4, 3
	s_cbranch_scc1 .Lbar_local
	s_mov_b64 s[4:5], exec
	buffer_wbl2 sc1
	s_waitcnt lgkmcnt(0)
	s_waitcnt vmcnt(0)
	v_mbcnt_lo_u32_b32 v0, s4, 0
	v_mbcnt_hi_u32_b32 v0, s5, v0
	v_cmp_eq_u32_e32 vcc, 0, v0
	s_and_saveexec_b64 s[6:7], vcc
	s_cbranch_execz .LBB0_1265
	s_bcnt1_i32_b64 s4, s[4:5]
	v_mov_b32_e32 v3, s4
	global_atomic_add v3, v191, v3, s[80:81] offset:1024 sc0

; __device__ __forceinline__ unsigned xb_add(unsigned* p, unsigned v) { return __hip_atomic_fetch_add(p, v, __ATOMIC_RELAXED, __HIP_MEMORY_SCOPE_AGENT); }
; __device__ __forceinline__ void xcd_barrier(const XcdBarrier& b) {
;     ...
;             __builtin_amdgcn_fence(__ATOMIC_ACQUIRE, "agent");
;             xb_add(&bar[XB_XGEN(b.x)], 1u);
;             asm volatile("s_waitcnt vmcnt(0)" ::: "memory");
.Lbar_local:
	s_mov_b64 s[4:5], exec
	v_mbcnt_lo_u32_b32 v0, s4, 0
	v_mbcnt_hi_u32_b32 v0, s5, v0
	v_cmp_eq_u32_e32 vcc, 0, v0
	s_waitcnt vmcnt(0)
	buffer_inv sc1
	s_and_saveexec_b64 s[6:7], vcc
	s_cbranch_execnz .LBB0_1280
	s_getpc_b64 s[98:99]
